# prep window-output copy (O_KS/O_VS rows 0..123, final outputs only) relocated to end of UP on idle WGs>=216, unrolled, sc1 stores
# speedup vs baseline: 1.0107x; 1.0107x over previous
; __device__ __forceinline__ void prep_phase(const Params& p, char* lds) {
;     ...
;     for (int i = gt; i < 128 * 124 * 32; i += NGT) {
;       const int c4 = i & 31, w = (i >> 5) % 124, b = i / (124 * 32);
;       const size_t so = ((size_t)b * 128 + w + 4) * 128 + c4 * 4, dof = ((size_t)b * 128 + w) * 128 + c4 * 4;
;       *(f32x4*)(p.out + O_KS + dof) = *(const f32x4*)(ck + so);
;       *(f32x4*)(p.out + O_VS + dof) = *(const f32x4*)(cv + so);
;     }
.LBB0_1103:
	s_waitcnt vmcnt(0)
	s_barrier
	v_readlane_b32 s98, v244, 33
	s_nop 3
	s_cmp_eq_u32 s33, 0x100
	s_cselect_b32 s99, 216, 0
	s_cmp_lt_u32 s98, s99
	s_cbranch_scc1 .Lwin_skip
	v_writelane_b32 v246, s0, 0
	v_writelane_b32 v246, s1, 1
	v_writelane_b32 v246, s2, 2
	v_writelane_b32 v246, s3, 3
	v_writelane_b32 v246, s4, 4
	v_writelane_b32 v246, s5, 5
	v_writelane_b32 v246, s6, 6
	v_writelane_b32 v246, s7, 7
	v_writelane_b32 v246, s8, 8
	v_writelane_b32 v246, s9, 9
	v_writelane_b32 v246, s10, 10
	v_writelane_b32 v246, s11, 11
	v_writelane_b32 v246, s12, 12
	v_writelane_b32 v246, s13, 13
	v_writelane_b32 v246, s14, 14
	v_writelane_b32 v246, s15, 15
	s_sub_u32 s98, s98, s99
	v_lshl_or_b32 v245, s98, 9, v0
	s_sub_u32 s100, s33, s99
	s_lshl_b32 s101, s100, 9
	v_readlane_b32 s12, v244, 18
	v_readlane_b32 s13, v244, 19
	v_readlane_b32 s14, v244, 20
	v_readlane_b32 s15, v244, 21
	v_readlane_b32 s8, v244, 0
	v_readlane_b32 s9, v244, 1
	s_nop 1
	s_add_u32 s4, s8, 0x4300000
	s_addc_u32 s5, s9, 0
	s_add_u32 s6, s8, 0x4b00000
	s_addc_u32 s7, s9, 0
	v_mov_b32_e32 v104, v245
	v_mov_b32_e32 v100, 0x2108422
.Lwin_l5:
	v_mov_b32_e32 v105, s101
	v_mad_u32_u24 v105, v105, 0, v104
	v_and_b32_e32 v103, 31, v105
	v_lshrrev_b32_e32 v102, 5, v105
	v_mul_hi_u32 v101, v102, v100
	v_mul_u32_u24_e32 v107, 0x7c, v101
	v_sub_u32_e32 v102, v102, v107
	v_lshlrev_b32_e32 v103, 4, v103
	v_lshl_add_u32 v103, v102, 9, v103
	v_lshl_add_u32 v107, v101, 16, v103
	v_add_u32_e32 v106, 0x800, v107
	v_mov_b32_e32 v109, s101
	v_mad_u32_u24 v109, v109, 1, v104
	v_and_b32_e32 v103, 31, v109
	v_lshrrev_b32_e32 v102, 5, v109
	v_mul_hi_u32 v101, v102, v100
	v_mul_u32_u24_e32 v111, 0x7c, v101
	v_sub_u32_e32 v102, v102, v111
	v_lshlrev_b32_e32 v103, 4, v103
	v_lshl_add_u32 v103, v102, 9, v103
	v_lshl_add_u32 v111, v101, 16, v103
	v_add_u32_e32 v110, 0x800, v111
	v_mov_b32_e32 v113, s101
	v_mad_u32_u24 v113, v113, 2, v104
	v_and_b32_e32 v103, 31, v113
	v_lshrrev_b32_e32 v102, 5, v113
	v_mul_hi_u32 v101, v102, v100
	v_mul_u32_u24_e32 v115, 0x7c, v101
	v_sub_u32_e32 v102, v102, v115
	v_lshlrev_b32_e32 v103, 4, v103
	v_lshl_add_u32 v103, v102, 9, v103
	v_lshl_add_u32 v115, v101, 16, v103
	v_add_u32_e32 v114, 0x800, v115
	v_mov_b32_e32 v117, s101
	v_mad_u32_u24 v117, v117, 3, v104
	v_and_b32_e32 v103, 31, v117
	v_lshrrev_b32_e32 v102, 5, v117
	v_mul_hi_u32 v101, v102, v100
	v_mul_u32_u24_e32 v119, 0x7c, v101
	v_sub_u32_e32 v102, v102, v119
	v_lshlrev_b32_e32 v103, 4, v103
	v_lshl_add_u32 v103, v102, 9, v103
	v_lshl_add_u32 v119, v101, 16, v103
	v_add_u32_e32 v118, 0x800, v119
	v_mov_b32_e32 v121, s101
	v_mad_u32_u24 v121, v121, 4, v104
	v_and_b32_e32 v103, 31, v121
	v_lshrrev_b32_e32 v102, 5, v121
	v_mul_hi_u32 v101, v102, v100
	v_mul_u32_u24_e32 v123, 0x7c, v101
	v_sub_u32_e32 v102, v102, v123
	v_lshlrev_b32_e32 v103, 4, v103
	v_lshl_add_u32 v103, v102, 9, v103
	v_lshl_add_u32 v123, v101, 16, v103
	v_add_u32_e32 v122, 0x800, v123
	v_mov_b32_e32 v125, s101
	v_mad_u32_u24 v125, v125, 5, v104
	v_and_b32_e32 v103, 31, v125
	v_lshrrev_b32_e32 v102, 5, v125
	v_mul_hi_u32 v101, v102, v100
	v_mul_u32_u24_e32 v127, 0x7c, v101
	v_sub_u32_e32 v102, v102, v127
	v_lshlrev_b32_e32 v103, 4, v103
	v_lshl_add_u32 v103, v102, 9, v103
	v_lshl_add_u32 v127, v101, 16, v103
	v_add_u32_e32 v126, 0x800, v127
	v_cmp_gt_u32_e32 vcc, 0x7c000, v105
	s_and_saveexec_b64 s[10:11], vcc
	global_load_dwordx4 v[132:135], v106, s[12:13]
	global_load_dwordx4 v[136:139], v106, s[14:15]
	s_or_b64 exec, exec, s[10:11]
	v_cmp_gt_u32_e32 vcc, 0x7c000, v109
	s_and_saveexec_b64 s[10:11], vcc
	global_load_dwordx4 v[140:143], v110, s[12:13]
	global_load_dwordx4 v[144:147], v110, s[14:15]
	s_or_b64 exec, exec, s[10:11]
	v_cmp_gt_u32_e32 vcc, 0x7c000, v113
	s_and_saveexec_b64 s[10:11], vcc
	global_load_dwordx4 v[148:151], v114, s[12:13]
	global_load_dwordx4 v[152:155], v114, s[14:15]
	s_or_b64 exec, exec, s[10:11]
	v_cmp_gt_u32_e32 vcc, 0x7c000, v117
	s_and_saveexec_b64 s[10:11], vcc
	global_load_dwordx4 v[156:159], v118, s[12:13]
	global_load_dwordx4 v[160:163], v118, s[14:15]
	s_or_b64 exec, exec, s[10:11]
	v_cmp_gt_u32_e32 vcc, 0x7c000, v121
	s_and_saveexec_b64 s[10:11], vcc
	global_load_dwordx4 v[164:167], v122, s[12:13]
	global_load_dwordx4 v[168:171], v122, s[14:15]
	s_or_b64 exec, exec, s[10:11]
	v_cmp_gt_u32_e32 vcc, 0x7c000, v125
	s_and_saveexec_b64 s[10:11], vcc
	global_load_dwordx4 v[172:175], v126, s[12:13]
	global_load_dwordx4 v[176:179], v126, s[14:15]
	s_or_b64 exec, exec, s[10:11]
	s_waitcnt vmcnt(0)
	v_cmp_gt_u32_e32 vcc, 0x7c000, v105
	s_and_saveexec_b64 s[10:11], vcc
	global_store_dwordx4 v107, v[132:135], s[4:5] sc1
	global_store_dwordx4 v107, v[136:139], s[6:7] sc1
	s_or_b64 exec, exec, s[10:11]
	v_cmp_gt_u32_e32 vcc, 0x7c000, v109
	s_and_saveexec_b64 s[10:11], vcc
	global_store_dwordx4 v111, v[140:143], s[4:5] sc1
	global_store_dwordx4 v111, v[144:147], s[6:7] sc1
	s_or_b64 exec, exec, s[10:11]
	v_cmp_gt_u32_e32 vcc, 0x7c000, v113
	s_and_saveexec_b64 s[10:11], vcc
	global_store_dwordx4 v115, v[148:151], s[4:5] sc1
	global_store_dwordx4 v115, v[152:155], s[6:7] sc1
	s_or_b64 exec, exec, s[10:11]
	v_cmp_gt_u32_e32 vcc, 0x7c000, v117
	s_and_saveexec_b64 s[10:11], vcc
	global_store_dwordx4 v119, v[156:159], s[4:5] sc1
	global_store_dwordx4 v119, v[160:163], s[6:7] sc1
	s_or_b64 exec, exec, s[10:11]
	v_cmp_gt_u32_e32 vcc, 0x7c000, v121
	s_and_saveexec_b64 s[10:11], vcc
	global_store_dwordx4 v123, v[164:167], s[4:5] sc1
	global_store_dwordx4 v123, v[168:171], s[6:7] sc1
	s_or_b64 exec, exec, s[10:11]
	v_cmp_gt_u32_e32 vcc, 0x7c000, v125
	s_and_saveexec_b64 s[10:11], vcc
	global_store_dwordx4 v127, v[172:175], s[4:5] sc1
	global_store_dwordx4 v127, v[176:179], s[6:7] sc1
	s_or_b64 exec, exec, s[10:11]
	v_mov_b32_e32 v103, s101
	v_mad_u32_u24 v104, v103, 6, v104
	v_cmp_gt_u32_e32 vcc, 0x7c000, v104
	s_cbranch_vccnz .Lwin_l5
	v_readlane_b32 s0, v246, 0
	v_readlane_b32 s1, v246, 1
	v_readlane_b32 s2, v246, 2
	v_readlane_b32 s3, v246, 3
	v_readlane_b32 s4, v246, 4
	v_readlane_b32 s5, v246, 5
	v_readlane_b32 s6, v246, 6
	v_readlane_b32 s7, v246, 7
	v_readlane_b32 s8, v246, 8
	v_readlane_b32 s9, v246, 9
	v_readlane_b32 s10, v246, 10
	v_readlane_b32 s11, v246, 11
	v_readlane_b32 s12, v246, 12
	v_readlane_b32 s13, v246, 13
	v_readlane_b32 s14, v246, 14
	v_readlane_b32 s15, v246, 15
	s_waitcnt vmcnt(0)
	s_barrier
.Lwin_skip:
	s_mov_b64 s[6:7], exec
	v_readlane_b32 s8, v244, 12
	v_readlane_b32 s9, v244, 13
	s_and_b64 s[8:9], s[6:7], s[8:9]
	s_mov_b64 exec, s[8:9]
	s_cbranch_execz .LBB0_1155
	s_add_i32 s3, 0, 0x20000
	v_mov_b32_e32 v2, s3
	s_waitcnt vmcnt(0) expcnt(0) lgkmcnt(0)
	ds_read_b32 v4, v2
	s_add_i32 s3, 0, 0x20004
	v_mov_b32_e32 v2, s3
	ds_read_b32 v2, v2
	s_waitcnt lgkmcnt(1)
	v_cmp_ne_u32_e32 vcc, 0, v4
	s_cbranch_vccnz .LBB0_1119
	v_readlane_b32 s10, v244, 31
	v_readlane_b32 s11, v244, 32
	s_load_dwordx2 s[8:9], s[10:11], 0x4
	s_mov_b32 s3, 1
	v_mov_b32_e32 v18, 0
	s_waitcnt lgkmcnt(0)
	s_mul_i32 s14, s8, s33
	s_mul_i32 s14, s14, s9
	s_branch .LBB0_1107
